# diff-attn loop: softmax part1 (max/scale) hoisted into PV MFMA shadow, counted lgkmcnt V reads, exps cover ds_write latency
# speedup vs baseline: 1.0111x; 1.0111x over previous
; __device__ __forceinline__ void finishSM(f32x16& p0, f32x16& p1, float alpha, float& l_reg, bf16x8& pa0, bf16x8& pa1, bf16x8& pa2, bf16x8& pa3) {
;     for (int r = 0; r < 16; ++r) p1[r] = __builtin_amdgcn_exp2f(p1[r]);
;     float ps = 0; for (int r = 0; r < 16; ++r) ps += p0[r]; for (int r = 0; r < 16; ++r) ps += p1[r];
;     { auto rr = __builtin_amdgcn_permlane32_swap(__float_as_uint(ps), __float_as_uint(ps), false, false);
;       ps = __uint_as_float(rr[0]) + __uint_as_float(rr[1]); }
;     l_reg = l_reg * alpha + ps;
;     ...
;     PK4(p0, 0, pa0); PK4(p0, 8, pa1); PK4(p1, 0, pa2); PK4(p1, 8, pa3);
;     ...
; }
; template <int KB, bool SK>
; __device__ __forceinline__ void qkt(f32x16& p0, f32x16& p1, const char* K_lds, int r32, int hi, const bf16x8* qr, bool act) {
;     if (SK && !act) { const float NEG = -__builtin_inff();
; #pragma unroll
;         for (int r = 0; r < 16; ++r) { p0[r] = NEG; p1[r] = NEG; } return; }
;     p0 = f32x16{}; p1 = f32x16{};
;     const char* kb[4];
; #pragma unroll
;     for (int dd = 0; dd < 4; ++dd) kb[dd] = K_lds + KB * SHM_K + KSWZ(r32, (dd * 16 + hi * 8) * 2);
; #pragma unroll
;     for (int d0 = 0; d0 < 8; ++d0) { const char* a = kb[d0 & 3] + (d0 >> 2) * 128;
;         bf16x8 b0 = *reinterpret_cast<const bf16x8*>(a);
;         bf16x8 b1 = *reinterpret_cast<const bf16x8*>(a + 32 * 256);
;         const bf16x8 qf = qr[d0];
;         p0 = __builtin_amdgcn_mfma_f32_32x32x16_bf16(b0, qf, p0, 0, 0, 0);
;         p1 = __builtin_amdgcn_mfma_f32_32x32x16_bf16(b1, qf, p1, 0, 0, 0); }
; }
.LBB0_1129:
	ds_read_b128 v[66:69], v211 offset:49152
	ds_read_b128 v[102:105], v211 offset:49280
	v_add_f32_e32 v179, 0, v170
	v_add_f32_e32 v179, v171, v179
	v_add_f32_e32 v179, v172, v179
	s_waitcnt lgkmcnt(1)
	v_mfma_f32_32x32x16_bf16 v[86:101], v[66:69], v[158:161], 0
	ds_read_b128 v[66:69], v211 offset:57344
	ds_read_b128 v[106:109], v211 offset:57472
	v_add_f32_e32 v179, v173, v179
	v_add_f32_e32 v179, v174, v179
	v_add_f32_e32 v179, v176, v179
	v_add_f32_e32 v179, v175, v179
	v_add_f32_e32 v179, v177, v179
	v_add_f32_e32 v179, v162, v179
	s_waitcnt lgkmcnt(1)
	v_mfma_f32_32x32x16_bf16 v[70:85], v[66:69], v[158:161], 0
	ds_read_b128 v[66:69], v212 offset:49152
	ds_read_b128 v[110:113], v212 offset:57344
	ds_read_b128 v[180:183], v212 offset:49280
	v_add_f32_e32 v179, v163, v179
	v_exp_f32_e32 v126, v126
	v_exp_f32_e32 v127, v127
	v_exp_f32_e32 v124, v124
	v_exp_f32_e32 v125, v125
	s_waitcnt lgkmcnt(2)
	v_mfma_f32_32x32x16_bf16 v[86:101], v[66:69], v[154:157], v[86:101]
	ds_read_b128 v[66:69], v212 offset:57472
	ds_read_b128 v[184:187], v213 offset:49152
	ds_read_b128 v[188:191], v213 offset:49280
	ds_read_b128 v[224:227], v213 offset:57344
	ds_read_b128 v[228:231], v213 offset:57472
	ds_read_b128 v[232:235], v214 offset:49152
	ds_read_b128 v[236:239], v214 offset:49280
	v_exp_f32_e32 v120, v120
	v_exp_f32_e32 v121, v121
	v_exp_f32_e32 v116, v116
	v_exp_f32_e32 v117, v117
	v_exp_f32_e32 v114, v114
	v_exp_f32_e32 v115, v115
	s_waitcnt lgkmcnt(8)
	v_mfma_f32_32x32x16_bf16 v[70:85], v[110:113], v[154:157], v[70:85]
	ds_read_b128 v[110:113], v214 offset:57344
	ds_read_b128 v[240:243], v214 offset:57472
	v_exp_f32_e32 v128, v128
	v_exp_f32_e32 v129, v129
	v_exp_f32_e32 v122, v122
	v_exp_f32_e32 v123, v123
	v_exp_f32_e32 v118, v118
	v_exp_f32_e32 v119, v119
	s_waitcnt lgkmcnt(7)
	v_mfma_f32_32x32x16_bf16 v[86:101], v[184:187], v[150:153], v[86:101]
	s_add_i32 s4, s26, 0xffffff81
	s_sub_i32 s5, s26, 64
	s_waitcnt lgkmcnt(5)
	v_mfma_f32_32x32x16_bf16 v[70:85], v[224:227], v[150:153], v[70:85]
	s_waitcnt lgkmcnt(3)
	v_mfma_f32_32x32x16_bf16 v[86:101], v[232:235], v[134:137], v[86:101]
	s_waitcnt lgkmcnt(1)
	v_mfma_f32_32x32x16_bf16 v[70:85], v[110:113], v[134:137], v[70:85]
	v_add_f32_e32 v110, v164, v179
	v_add_f32_e32 v110, v166, v110
	v_add_f32_e32 v110, v165, v110
	v_add_f32_e32 v110, v167, v110
	v_add_f32_e32 v110, v168, v110
	v_add_f32_e32 v110, v169, v110
	v_add_f32_e32 v110, v126, v110
	v_mfma_f32_32x32x16_bf16 v[86:101], v[102:105], v[138:141], v[86:101]
	v_add_f32_e32 v102, v127, v110
	v_add_f32_e32 v102, v124, v102
	v_add_f32_e32 v102, v125, v102
	v_add_f32_e32 v102, v120, v102
	v_add_f32_e32 v102, v121, v102
	v_add_f32_e32 v102, v116, v102
	v_add_f32_e32 v102, v117, v102
	v_mfma_f32_32x32x16_bf16 v[70:85], v[106:109], v[138:141], v[70:85]
	v_add_f32_e32 v102, v114, v102
	v_add_f32_e32 v102, v115, v102
	v_add_f32_e32 v102, v128, v102
	v_add_f32_e32 v102, v129, v102
	v_add_f32_e32 v102, v122, v102
	v_add_f32_e32 v102, v123, v102
	v_add_f32_e32 v102, v118, v102
	v_mfma_f32_32x32x16_bf16 v[86:101], v[180:183], v[142:145], v[86:101]
	v_add_f32_e32 v223, v119, v102
	v_mov_b32_e32 v224, v223
	s_nop 1
	v_permlane32_swap_b32_e32 v223, v224
	v_cvt_pk_bf16_f32 v102, v170, v171
	v_cvt_pk_bf16_f32 v103, v172, v173
	v_cvt_pk_bf16_f32 v104, v174, v176
	v_mfma_f32_32x32x16_bf16 v[70:85], v[66:69], v[142:145], v[70:85]
	v_cvt_pk_bf16_f32 v105, v175, v177
	v_cvt_pk_bf16_f32 v66, v162, v163
	v_cvt_pk_bf16_f32 v67, v164, v166
	v_cvt_pk_bf16_f32 v68, v165, v167
	v_cvt_pk_bf16_f32 v69, v168, v169
	v_cvt_pk_bf16_f32 v106, v126, v127
	v_cvt_pk_bf16_f32 v107, v124, v125
	v_mfma_f32_32x32x16_bf16 v[86:101], v[188:191], v[146:149], v[86:101]
	v_cvt_pk_bf16_f32 v108, v120, v121
	v_cvt_pk_bf16_f32 v109, v116, v117
	v_cvt_pk_bf16_f32 v110, v114, v115
	v_cvt_pk_bf16_f32 v111, v128, v129
	v_cvt_pk_bf16_f32 v112, v122, v123
	v_cvt_pk_bf16_f32 v113, v118, v119
	v_permlane32_swap_b32_e32 v102, v104
	v_mfma_f32_32x32x16_bf16 v[70:85], v[228:231], v[146:149], v[70:85]
	v_permlane32_swap_b32_e32 v103, v105
	v_permlane32_swap_b32_e32 v66, v68
	v_permlane32_swap_b32_e32 v67, v69
	v_permlane32_swap_b32_e32 v106, v108
	v_mfma_f32_32x32x16_bf16 v[86:101], v[236:239], v[130:133], v[86:101]
	v_permlane32_swap_b32_e32 v107, v109
	v_permlane32_swap_b32_e32 v110, v112
	v_permlane32_swap_b32_e32 v111, v113
	s_waitcnt lgkmcnt(0)
	v_mfma_f32_32x32x16_bf16 v[70:85], v[240:243], v[130:133], v[70:85]
	v_lshlrev_b64 v[114:115], 1, v[194:195]
	v_add_u32_e32 v118, 0x1000, v194
	v_mov_b32_e32 v119, v195
	v_lshl_add_u64 v[116:117], s[42:43], 0, v[114:115]
	v_lshlrev_b64 v[118:119], 1, v[118:119]
	v_lshl_add_u64 v[114:115], s[22:23], 0, v[114:115]
	v_lshl_add_u64 v[120:121], s[42:43], 0, v[118:119]
	global_load_dwordx4 v[162:165], v[116:117], off
	global_load_dwordx4 v[166:169], v[120:121], off
	v_lshl_add_u64 v[116:117], s[22:23], 0, v[118:119]
	global_load_dwordx4 v[170:173], v[114:115], off
	global_load_dwordx4 v[174:177], v[116:117], off
	s_cmp_le_i32 s5, s13
	s_cselect_b64 s[52:53], -1, 0
	s_cmp_gt_i32 s4, s15
	s_cselect_b64 s[4:5], -1, 0
	s_and_b64 s[4:5], s[52:53], s[4:5]
	s_and_b64 vcc, exec, s[4:5]
	v_add_u32_e32 v226, s80, v222
	ds_read_b64_tr_b16 v[114:115], v202 offset:0x0
	ds_read_b64_tr_b16 v[116:117], v202 offset:0x800
	ds_read_b64_tr_b16 v[118:119], v202 offset:0x1000
	ds_read_b64_tr_b16 v[120:121], v202 offset:0x1800
	ds_read_b64_tr_b16 v[122:123], v202 offset:0x2000
	ds_read_b64_tr_b16 v[124:125], v202 offset:0x2800
	ds_read_b64_tr_b16 v[126:127], v202 offset:0x3000
	ds_read_b64_tr_b16 v[128:129], v202 offset:0x3800
	s_cbranch_vccnz .Lh1_nomask
; __device__ __forceinline__ void mask_tile(f32x16& p0, f32x16& p1, int dq, unsigned W) {
;     const float NEG = -__builtin_inff();
; #pragma unroll
;     for (int r = 0; r < 16; ++r) {
;         const int c = (r & 3) + 8 * (r >> 2);
;         if ((unsigned)(dq - c) >= W) p0[r] = NEG;
;         if ((unsigned)(dq - c - 32) >= W) p1[r] = NEG;
;     }
; }
; __device__ __forceinline__ void partialSM(f32x16& p0, f32x16& p1, float& m_reg, float& mn, float& alpha) {
;     float pmax = p0[0]; for (int r = 1; r < 16; ++r) pmax = fmaxf(pmax, p0[r]); for (int r = 0; r < 16; ++r) pmax = fmaxf(pmax, p1[r]);
;     { auto rr = __builtin_amdgcn_permlane32_swap(__float_as_uint(pmax), __float_as_uint(pmax), false, false);
;       pmax = fmaxf(__uint_as_float(rr[0]), __uint_as_float(rr[1])); }
;     constexpr float C2 = 1.4426950408889634f * SCALE;
;     if (__builtin_expect(__all((pmax - m_reg) * SCALE <= THR), 1)) { mn = m_reg; alpha = 1.f; }
;     else { mn = fmaxf(m_reg, pmax); alpha = __builtin_amdgcn_exp2f((m_reg - mn) * C2); m_reg = mn; }
;     const float mnL = -mn * C2;
;     for (int r = 0; r < 16; ++r) p0[r] = fmaf(p0[r], C2, mnL); for (int r = 0; r < 16; ++r) p1[r] = fmaf(p1[r], C2, mnL);
;     for (int r = 0; r < 16; ++r) p0[r] = __builtin_amdgcn_exp2f(p0[r]);
; }
; template <int VB, bool SK>
; __device__ __forceinline__ void pv_tile(f32x16* o, int vb0, bf16x8 pa0, bf16x8 pa1, bf16x8 pa2, bf16x8 pa3, bool act) {
;     if (SK && !act) return;
;     ...
;     PV_D0(0); PV_D0(1); PV_D0(2); PV_D0(3);
	v_subrev_u32_e32 v240, 64, v226
	v_cmp_gt_u32_e32 vcc, s85, v240
	v_add_u32_e32 v240, 0xffffffa0, v226
	s_nop 0
	v_cndmask_b32_e32 v86, v215, v86, vcc
	v_cmp_gt_u32_e32 vcc, s85, v240
	v_add_u32_e32 v240, 0xffffffbf, v226
	s_nop 0
	v_cndmask_b32_e32 v70, v215, v70, vcc
	v_cmp_gt_u32_e32 vcc, s85, v240
	v_add_u32_e32 v240, 0xffffff9f, v226
	s_nop 0
	v_cndmask_b32_e32 v87, v215, v87, vcc
	v_cmp_gt_u32_e32 vcc, s85, v240
	v_add_u32_e32 v240, 0xffffffbe, v226
	s_nop 0
	v_cndmask_b32_e32 v71, v215, v71, vcc
	v_cmp_gt_u32_e32 vcc, s85, v240
	v_add_u32_e32 v240, 0xffffff9e, v226
	s_nop 0
	v_cndmask_b32_e32 v88, v215, v88, vcc
	v_cmp_gt_u32_e32 vcc, s85, v240
	v_add_u32_e32 v240, 0xffffffbd, v226
	s_nop 0
	v_cndmask_b32_e32 v72, v215, v72, vcc
	v_cmp_gt_u32_e32 vcc, s85, v240
	v_add_u32_e32 v240, 0xffffff9d, v226
	s_nop 0
	v_cndmask_b32_e32 v89, v215, v89, vcc
	v_cmp_gt_u32_e32 vcc, s85, v240
	v_add_u32_e32 v240, 0xffffffb8, v226
	s_nop 0
	v_cndmask_b32_e32 v73, v215, v73, vcc
	v_cmp_gt_u32_e32 vcc, s85, v240
	v_add_u32_e32 v240, 0xffffff98, v226
	s_nop 0
	v_cndmask_b32_e32 v90, v215, v90, vcc
	v_cmp_gt_u32_e32 vcc, s85, v240
	v_add_u32_e32 v240, 0xffffffb7, v226
	s_nop 0
	v_cndmask_b32_e32 v74, v215, v74, vcc
	v_cmp_gt_u32_e32 vcc, s85, v240
	v_add_u32_e32 v240, 0xffffff97, v226
	s_nop 0
	v_cndmask_b32_e32 v91, v215, v91, vcc
	v_cmp_gt_u32_e32 vcc, s85, v240
	v_add_u32_e32 v240, 0xffffffb6, v226
	s_nop 0
	v_cndmask_b32_e32 v75, v215, v75, vcc
	v_cmp_gt_u32_e32 vcc, s85, v240
	v_add_u32_e32 v240, 0xffffff96, v226
	s_nop 0
	v_cndmask_b32_e32 v92, v215, v92, vcc
	v_cmp_gt_u32_e32 vcc, s85, v240
	v_add_u32_e32 v240, 0xffffffb5, v226
	s_nop 0
	v_cndmask_b32_e32 v76, v215, v76, vcc
	v_cmp_gt_u32_e32 vcc, s85, v240
	v_add_u32_e32 v240, 0xffffff95, v226
	s_nop 0
	v_cndmask_b32_e32 v93, v215, v93, vcc
	v_cmp_gt_u32_e32 vcc, s85, v240
	v_add_u32_e32 v240, 0xffffffb0, v226
	s_nop 0
	v_cndmask_b32_e32 v77, v215, v77, vcc
	v_cmp_gt_u32_e32 vcc, s85, v240
	v_add_u32_e32 v240, 0xffffff90, v226
	s_nop 0
	v_cndmask_b32_e32 v94, v215, v94, vcc
	v_cmp_gt_u32_e32 vcc, s85, v240
	v_add_u32_e32 v240, 0xffffffaf, v226
	s_nop 0
	v_cndmask_b32_e32 v78, v215, v78, vcc
	v_cmp_gt_u32_e32 vcc, s85, v240
	v_add_u32_e32 v240, 0xffffff8f, v226
	s_nop 0
	v_cndmask_b32_e32 v95, v215, v95, vcc
	v_cmp_gt_u32_e32 vcc, s85, v240
	v_add_u32_e32 v240, 0xffffffae, v226
	s_nop 0
	v_cndmask_b32_e32 v79, v215, v79, vcc
	v_cmp_gt_u32_e32 vcc, s85, v240
	v_add_u32_e32 v240, 0xffffff8e, v226
	s_nop 0
	v_cndmask_b32_e32 v96, v215, v96, vcc
	v_cmp_gt_u32_e32 vcc, s85, v240
	v_add_u32_e32 v240, 0xffffffad, v226
	s_nop 0
	v_cndmask_b32_e32 v80, v215, v80, vcc
	v_cmp_gt_u32_e32 vcc, s85, v240
	v_add_u32_e32 v240, 0xffffff8d, v226
	s_nop 0
	v_cndmask_b32_e32 v97, v215, v97, vcc
	v_cmp_gt_u32_e32 vcc, s85, v240
	v_add_u32_e32 v240, 0xffffffa8, v226
	s_nop 0
	v_cndmask_b32_e32 v81, v215, v81, vcc
	v_cmp_gt_u32_e32 vcc, s85, v240
	v_add_u32_e32 v240, 0xffffff88, v226
	s_nop 0
	v_cndmask_b32_e32 v98, v215, v98, vcc
	v_cmp_gt_u32_e32 vcc, s85, v240
	v_add_u32_e32 v240, 0xffffffa7, v226
	s_nop 0
	v_cndmask_b32_e32 v82, v215, v82, vcc
	v_cmp_gt_u32_e32 vcc, s85, v240
	v_add_u32_e32 v240, 0xffffff87, v226
	s_nop 0
	v_cndmask_b32_e32 v99, v215, v99, vcc
	v_cmp_gt_u32_e32 vcc, s85, v240
	v_add_u32_e32 v240, 0xffffffa6, v226
	s_nop 0
	v_cndmask_b32_e32 v83, v215, v83, vcc
	v_cmp_gt_u32_e32 vcc, s85, v240
	v_add_u32_e32 v240, 0xffffff86, v226
	s_nop 0
	v_cndmask_b32_e32 v100, v215, v100, vcc
	v_cmp_gt_u32_e32 vcc, s85, v240
	v_add_u32_e32 v240, 0xffffffa5, v226
	s_nop 0
	v_cndmask_b32_e32 v84, v215, v84, vcc
	v_cmp_gt_u32_e32 vcc, s85, v240
	v_add_u32_e32 v240, 0xffffff85, v226
	s_nop 0
	v_cndmask_b32_e32 v101, v215, v101, vcc
	v_cmp_gt_u32_e32 vcc, s85, v240
	s_nop 1
	v_cndmask_b32_e32 v85, v215, v85, vcc
.Lh1_nomask:
	v_max_f32_e32 v240, v87, v87
	v_max_f32_e32 v241, v86, v86
	v_max_f32_e32 v240, v241, v240
	v_max3_f32 v240, v240, v88, v89
	v_max3_f32 v240, v240, v90, v91
	s_waitcnt lgkmcnt(6)
	v_mfma_f32_32x32x16_bf16 v[34:49], v[102:105], v[114:117], v[34:49]
	ds_read_b64_tr_b16 v[114:115], v202 offset:0x200
	ds_read_b64_tr_b16 v[116:117], v202 offset:0xa00
	v_max3_f32 v240, v240, v92, v93
	v_max3_f32 v240, v240, v94, v95
	v_max3_f32 v240, v240, v96, v97
	v_max3_f32 v240, v240, v98, v99
	v_max3_f32 v240, v240, v100, v101
	s_waitcnt lgkmcnt(6)
	v_mfma_f32_32x32x16_bf16 v[34:49], v[66:69], v[118:121], v[34:49]
	ds_read_b64_tr_b16 v[118:119], v202 offset:0x1200
	ds_read_b64_tr_b16 v[120:121], v202 offset:0x1a00
	v_max3_f32 v240, v240, v70, v71
	v_max3_f32 v240, v240, v72, v73
	v_max3_f32 v240, v240, v74, v75
	v_max3_f32 v240, v240, v76, v77
	v_max3_f32 v240, v240, v78, v79
	s_waitcnt lgkmcnt(6)
	v_mfma_f32_32x32x16_bf16 v[34:49], v[106:109], v[122:125], v[34:49]
	ds_read_b64_tr_b16 v[122:123], v202 offset:0x2200
	ds_read_b64_tr_b16 v[124:125], v202 offset:0x2a00
	v_max3_f32 v240, v240, v80, v81
	v_max3_f32 v240, v240, v82, v83
	v_max3_f32 v240, v240, v84, v85
	v_mov_b32_e32 v241, v240
	s_waitcnt lgkmcnt(6)
	v_mfma_f32_32x32x16_bf16 v[34:49], v[110:113], v[126:129], v[34:49]
	ds_read_b64_tr_b16 v[126:127], v202 offset:0x3200
	ds_read_b64_tr_b16 v[128:129], v202 offset:0x3a00
	s_nop 1
	v_permlane32_swap_b32_e32 v240, v241
	v_max_f32_e32 v241, v241, v241
	v_max_f32_e32 v240, v240, v240
	v_max_f32_e32 v240, v240, v241
	s_waitcnt lgkmcnt(6)
	v_mfma_f32_32x32x16_bf16 v[50:65], v[102:105], v[114:117], v[50:65]
	ds_read_b64_tr_b16 v[114:115], v202 offset:0x400
	ds_read_b64_tr_b16 v[116:117], v202 offset:0xc00
	v_max_f32_e32 v242, v178, v178
	v_sub_f32_e32 v241, v240, v178
	v_max_f32_e32 v240, v242, v240
	v_sub_f32_e32 v242, v178, v240
	s_waitcnt lgkmcnt(6)
; #define SBAR() __builtin_amdgcn_sched_barrier(0)
; #define VMW() asm volatile("s_waitcnt vmcnt(0)" ::: "memory")
; #define SLOAD_H(Kp, Vp, k0) do { S.st_v0 = load8<TIn>(ROW(Vp, k0, sr)); S.st_v1 = load8<TIn>(ROW(Vp, k0, 32 + sr));              \
;                          S.st_k0 = load8<TIn>(ROW(Kp, k0, sr)); S.st_k1 = load8<TIn>(ROW(Kp, k0, 32 + sr)); } while (0)
; #define SWRITE_H(bf) do { SWRITE_HV(bf); SWRITE_HK(bf); } while (0)
; __device__ __forceinline__ void partialSM(f32x16& p0, f32x16& p1, float& m_reg, float& mn, float& alpha) {
;     float pmax = p0[0]; for (int r = 1; r < 16; ++r) pmax = fmaxf(pmax, p0[r]); for (int r = 0; r < 16; ++r) pmax = fmaxf(pmax, p1[r]);
;     { auto rr = __builtin_amdgcn_permlane32_swap(__float_as_uint(pmax), __float_as_uint(pmax), false, false);
;       pmax = fmaxf(__uint_as_float(rr[0]), __uint_as_float(rr[1])); }
;     constexpr float C2 = 1.4426950408889634f * SCALE;
;     if (__builtin_expect(__all((pmax - m_reg) * SCALE <= THR), 1)) { mn = m_reg; alpha = 1.f; }
;     else { mn = fmaxf(m_reg, pmax); alpha = __builtin_amdgcn_exp2f((m_reg - mn) * C2); m_reg = mn; }
;     const float mnL = -mn * C2;
;     for (int r = 0; r < 16; ++r) p0[r] = fmaf(p0[r], C2, mnL); for (int r = 0; r < 16; ++r) p1[r] = fmaf(p1[r], C2, mnL);
;     for (int r = 0; r < 16; ++r) p0[r] = __builtin_amdgcn_exp2f(p0[r]);
; }
; template <class TIn, class TOut>
; __device__ __forceinline__ void causal_swa_block(const BlockRef<TIn, TOut>& cur, const BlockRef<TIn, TOut>& nxt, int skv, int W, char* lds, Seam<TIn>& S) {
;     ...
;     constexpr int NQL = F32 ? 16 : 8;
;     constexpr bool SK = WSKIP && !F32;
;     ...
;     f32x16 pA0, pA1, pB0, pB1; float mnA, mnB, alA, alB; bf16x8 pa0, pa1, pa2, pa3;
;     if constexpr (F32) { VMW(); SWRITE_VF(0); SBAR(); } else { SWRITE_HV(0); SBAR(); }
;     if (NT > 1) { if constexpr (F32) SLOAD_F((const float*)Kh, KBASE(1)); else SLOAD_H(Kh, Vh, KBASE(1)); }
;     SBAR(); qkt<0, SK>(pA0, pA1, K_lds, r32, hi, S.qr, ACT(0));
;     if constexpr (F32) { if (NT > 1) { VMW(); SWRITE_KF(1); SBAR(); SLOAD_F((const float*)Vh, KBASE(1)); } }
;     MASKT(pA0, pA1, 0); partialSM(pA0, pA1, m_reg, mnA, alA);
;     if (NT > 1) { VMW(); if constexpr (F32) { SWRITE_VF(1); SBAR(); if (NT > 2) SLOAD_F((const float*)Kh, KBASE(2)); } else SWRITE_H(1); }
;     __syncthreads();
	v_mfma_f32_32x32x16_bf16 v[50:65], v[66:69], v[118:121], v[50:65]
	ds_read_b64_tr_b16 v[118:119], v202 offset:0x1400
	ds_read_b64_tr_b16 v[120:121], v202 offset:0x1c00
	v_mul_f32_e32 v242, 0x3e0293ee, v242
	v_mul_f32_e32 v241, 0x3db504f3, v241
	v_exp_f32_e32 v242, v242
	v_cmp_ge_f32_e32 vcc, s86, v241
	s_waitcnt lgkmcnt(6)
	v_mfma_f32_32x32x16_bf16 v[50:65], v[106:109], v[122:125], v[50:65]
	ds_read_b64_tr_b16 v[122:123], v202 offset:0x2400
	ds_read_b64_tr_b16 v[124:125], v202 offset:0x2c00
	s_cmp_eq_u64 vcc, exec
	s_cselect_b64 s[4:5], -1, 0
	v_cndmask_b32_e64 v227, v240, v178, s[4:5]
	v_cndmask_b32_e64 v225, v242, 1.0, s[4:5]
	v_mul_f32_e32 v178, 0xbe0293ee, v227
	v_cmp_gt_f32_e32 vcc, 1.0, v225
	s_waitcnt lgkmcnt(6)
	v_mfma_f32_32x32x16_bf16 v[50:65], v[110:113], v[126:129], v[50:65]
	ds_read_b64_tr_b16 v[126:127], v202 offset:0x3400
	ds_read_b64_tr_b16 v[128:129], v202 offset:0x3c00
	v_fmamk_f32 v228, v86, 0x3e0293ee, v178
	v_fmamk_f32 v229, v87, 0x3e0293ee, v178
	v_fmamk_f32 v230, v88, 0x3e0293ee, v178
	v_fmamk_f32 v231, v89, 0x3e0293ee, v178
	s_waitcnt lgkmcnt(6)
	v_mfma_f32_32x32x16_bf16 v[18:33], v[102:105], v[114:117], v[18:33]
	ds_read_b64_tr_b16 v[114:115], v202 offset:0x600
	ds_read_b64_tr_b16 v[116:117], v202 offset:0xe00
	v_fmamk_f32 v232, v90, 0x3e0293ee, v178
	v_fmamk_f32 v233, v91, 0x3e0293ee, v178
	v_fmamk_f32 v234, v92, 0x3e0293ee, v178
	v_fmamk_f32 v235, v93, 0x3e0293ee, v178
	s_waitcnt lgkmcnt(6)
	v_mfma_f32_32x32x16_bf16 v[18:33], v[66:69], v[118:121], v[18:33]
	ds_read_b64_tr_b16 v[118:119], v202 offset:0x1600
	ds_read_b64_tr_b16 v[120:121], v202 offset:0x1e00
	v_fmamk_f32 v236, v94, 0x3e0293ee, v178
	v_fmamk_f32 v237, v95, 0x3e0293ee, v178
	v_fmamk_f32 v238, v96, 0x3e0293ee, v178
	v_fmamk_f32 v239, v97, 0x3e0293ee, v178
	s_waitcnt lgkmcnt(6)
	v_mfma_f32_32x32x16_bf16 v[18:33], v[106:109], v[122:125], v[18:33]
	ds_read_b64_tr_b16 v[122:123], v202 offset:0x2600
	ds_read_b64_tr_b16 v[124:125], v202 offset:0x2e00
	v_fmamk_f32 v98, v98, 0x3e0293ee, v178
	v_fmamk_f32 v99, v99, 0x3e0293ee, v178
	v_fmamk_f32 v100, v100, 0x3e0293ee, v178
	v_fmamk_f32 v101, v101, 0x3e0293ee, v178
	s_waitcnt lgkmcnt(6)
	v_mfma_f32_32x32x16_bf16 v[18:33], v[110:113], v[126:129], v[18:33]
	ds_read_b64_tr_b16 v[126:127], v202 offset:0x3600
	ds_read_b64_tr_b16 v[128:129], v202 offset:0x3e00
	v_fmamk_f32 v86, v70, 0x3e0293ee, v178
	v_fmamk_f32 v95, v71, 0x3e0293ee, v178
	v_fmamk_f32 v96, v72, 0x3e0293ee, v178
	v_fmamk_f32 v97, v73, 0x3e0293ee, v178
	s_waitcnt lgkmcnt(6)
	v_mfma_f32_32x32x16_bf16 v[2:17], v[102:105], v[114:117], v[2:17]
	v_fmamk_f32 v179, v74, 0x3e0293ee, v178
	v_fmamk_f32 v87, v75, 0x3e0293ee, v178
	v_fmamk_f32 v88, v76, 0x3e0293ee, v178
	v_fmamk_f32 v89, v77, 0x3e0293ee, v178
	s_waitcnt lgkmcnt(4)
	v_mfma_f32_32x32x16_bf16 v[2:17], v[66:69], v[118:121], v[2:17]
	v_fmamk_f32 v90, v78, 0x3e0293ee, v178
	v_fmamk_f32 v91, v79, 0x3e0293ee, v178
	v_fmamk_f32 v92, v80, 0x3e0293ee, v178
	v_fmamk_f32 v93, v81, 0x3e0293ee, v178
	s_waitcnt lgkmcnt(2)
	v_mfma_f32_32x32x16_bf16 v[2:17], v[106:109], v[122:125], v[2:17]
	v_fmamk_f32 v94, v82, 0x3e0293ee, v178
	v_fmamk_f32 v180, v83, 0x3e0293ee, v178
	v_fmamk_f32 v181, v84, 0x3e0293ee, v178
	v_fmac_f32_e32 v178, 0x3e0293ee, v85
	s_waitcnt lgkmcnt(0)
	v_mfma_f32_32x32x16_bf16 v[2:17], v[110:113], v[126:129], v[2:17]
	s_barrier
	s_waitcnt vmcnt(0)
	ds_write_b128 v209, v[162:165]
	ds_write_b128 v210, v[166:169]
	ds_write_b128 v217, v[170:173] offset:32768
	ds_write_b128 v217, v[174:177] offset:40960
	s_cbranch_vccz .Lh1_noresc
	s_and_saveexec_b64 s[52:53], s[0:1]
	ds_write_b32 v219, v225 offset:128
	s_or_b64 exec, exec, s[52:53]
	s_waitcnt lgkmcnt(0)
	ds_read_b128 v[102:105], v218 offset:224
	ds_read_b128 v[106:109], v218 offset:192
	ds_read_b128 v[110:113], v218 offset:160
	ds_read_b128 v[114:117], v218 offset:128
	s_waitcnt lgkmcnt(3)
	v_pk_mul_f32 v[48:49], v[48:49], v[104:105]
	s_waitcnt lgkmcnt(2)
	v_pk_mul_f32 v[44:45], v[44:45], v[108:109]
	s_waitcnt lgkmcnt(1)
	v_pk_mul_f32 v[40:41], v[40:41], v[112:113]
	s_waitcnt lgkmcnt(0)
	v_pk_mul_f32 v[36:37], v[36:37], v[116:117]
	v_pk_mul_f32 v[46:47], v[46:47], v[102:103]
	v_pk_mul_f32 v[42:43], v[42:43], v[106:107]
	v_pk_mul_f32 v[38:39], v[38:39], v[110:111]
	v_pk_mul_f32 v[34:35], v[34:35], v[114:115]
	v_pk_mul_f32 v[64:65], v[64:65], v[104:105]
	v_pk_mul_f32 v[60:61], v[60:61], v[108:109]
	v_pk_mul_f32 v[56:57], v[56:57], v[112:113]
	v_pk_mul_f32 v[52:53], v[52:53], v[116:117]
	v_pk_mul_f32 v[62:63], v[62:63], v[102:103]
	v_pk_mul_f32 v[58:59], v[58:59], v[106:107]
	v_pk_mul_f32 v[54:55], v[54:55], v[110:111]
	v_pk_mul_f32 v[50:51], v[50:51], v[114:115]
	v_pk_mul_f32 v[32:33], v[32:33], v[104:105]
	v_pk_mul_f32 v[28:29], v[28:29], v[108:109]
	v_pk_mul_f32 v[24:25], v[24:25], v[112:113]
	v_pk_mul_f32 v[20:21], v[20:21], v[116:117]
	v_pk_mul_f32 v[30:31], v[30:31], v[102:103]
	v_pk_mul_f32 v[26:27], v[26:27], v[106:107]
	v_pk_mul_f32 v[22:23], v[22:23], v[110:111]
	v_pk_mul_f32 v[18:19], v[18:19], v[114:115]
	v_pk_mul_f32 v[16:17], v[16:17], v[104:105]
	v_pk_mul_f32 v[12:13], v[12:13], v[108:109]
	v_pk_mul_f32 v[8:9], v[8:9], v[112:113]
	v_pk_mul_f32 v[4:5], v[4:5], v[116:117]
	v_pk_mul_f32 v[14:15], v[14:15], v[102:103]
	v_pk_mul_f32 v[10:11], v[10:11], v[106:107]
	v_pk_mul_f32 v[6:7], v[6:7], v[110:111]
	v_pk_mul_f32 v[2:3], v[2:3], v[114:115]
; __device__ __forceinline__ void partialSM(f32x16& p0, f32x16& p1, float& m_reg, float& mn, float& alpha) {
;     ...
;     for (int r = 0; r < 16; ++r) p0[r] = fmaf(p0[r], C2, mnL); for (int r = 0; r < 16; ++r) p1[r] = fmaf(p1[r], C2, mnL);
;     for (int r = 0; r < 16; ++r) p0[r] = __builtin_amdgcn_exp2f(p0[r]);
; }
; __device__ __forceinline__ void finishSM(f32x16& p0, f32x16& p1, float alpha, float& l_reg, bf16x8& pa0, bf16x8& pa1, bf16x8& pa2, bf16x8& pa3) {
;     for (int r = 0; r < 16; ++r) p1[r] = __builtin_amdgcn_exp2f(p1[r]);
;     float ps = 0; for (int r = 0; r < 16; ++r) ps += p0[r]; for (int r = 0; r < 16; ++r) ps += p1[r];
;     { auto rr = __builtin_amdgcn_permlane32_swap(__float_as_uint(ps), __float_as_uint(ps), false, false);
;       ps = __uint_as_float(rr[0]) + __uint_as_float(rr[1]); }
;     l_reg = l_reg * alpha + ps;
;     ...
;     PK4(p0, 0, pa0); PK4(p0, 8, pa1); PK4(p1, 0, pa2); PK4(p1, 8, pa3);
;     ...
; }
; template <int KB, bool SK>
; __device__ __forceinline__ void qkt(f32x16& p0, f32x16& p1, const char* K_lds, int r32, int hi, const bf16x8* qr, bool act) {
;     if (SK && !act) { const float NEG = -__builtin_inff();
; #pragma unroll
;         for (int r = 0; r < 16; ++r) { p0[r] = NEG; p1[r] = NEG; } return; }
;     p0 = f32x16{}; p1 = f32x16{};
;     const char* kb[4];
; #pragma unroll
;     for (int dd = 0; dd < 4; ++dd) kb[dd] = K_lds + KB * SHM_K + KSWZ(r32, (dd * 16 + hi * 8) * 2);
; #pragma unroll
;     for (int d0 = 0; d0 < 8; ++d0) { const char* a = kb[d0 & 3] + (d0 >> 2) * 128;
;         bf16x8 b0 = *reinterpret_cast<const bf16x8*>(a);
;         bf16x8 b1 = *reinterpret_cast<const bf16x8*>(a + 32 * 256);
;         const bf16x8 qf = qr[d0];
;         p0 = __builtin_amdgcn_mfma_f32_32x32x16_bf16(b0, qf, p0, 0, 0, 0);
;         p1 = __builtin_amdgcn_mfma_f32_32x32x16_bf16(b1, qf, p1, 0, 0, 0); }
; }
.Lh1_noresc:
	v_exp_f32_e32 v66, v228
	v_exp_f32_e32 v67, v229
	v_exp_f32_e32 v68, v230
	v_exp_f32_e32 v69, v231
	v_exp_f32_e32 v70, v232
	v_exp_f32_e32 v71, v233
	v_exp_f32_e32 v72, v234
	v_exp_f32_e32 v73, v235
	v_exp_f32_e32 v74, v236
	v_exp_f32_e32 v75, v237
	v_exp_f32_e32 v76, v238
	v_exp_f32_e32 v77, v239
	v_exp_f32_e32 v78, v98
	v_exp_f32_e32 v79, v99
	v_exp_f32_e32 v80, v100
	v_exp_f32_e32 v81, v101
	s_waitcnt lgkmcnt(0)
	s_barrier
	ds_read_b128 v[82:85], v211 offset:32768
	ds_read_b128 v[98:101], v211 offset:40960
	v_exp_f32_e32 v87, v87
	v_exp_f32_e32 v88, v88
	v_exp_f32_e32 v89, v89
	s_waitcnt lgkmcnt(1)
	v_mfma_f32_32x32x16_bf16 v[114:129], v[82:85], v[158:161], 0
	ds_read_b128 v[82:85], v212 offset:32768
	ds_read_b128 v[182:185], v212 offset:40960
	v_exp_f32_e32 v90, v90
	v_exp_f32_e32 v91, v91
	v_exp_f32_e32 v92, v92
	v_exp_f32_e32 v93, v93
	v_exp_f32_e32 v94, v94
	v_cvt_pk_bf16_f32 v189, v88, v89
	s_waitcnt lgkmcnt(2)
	v_mfma_f32_32x32x16_bf16 v[98:113], v[98:101], v[158:161], 0
	v_cvt_pk_bf16_f32 v190, v90, v91
	v_cvt_pk_bf16_f32 v191, v92, v93
	s_waitcnt lgkmcnt(1)
	v_mfma_f32_32x32x16_bf16 v[114:129], v[82:85], v[154:157], v[114:129]
	s_waitcnt lgkmcnt(0)
	v_mfma_f32_32x32x16_bf16 v[98:113], v[182:185], v[154:157], v[98:113]
	ds_read_b128 v[82:85], v213 offset:32768
	ds_read_b128 v[182:185], v213 offset:40960
	s_waitcnt lgkmcnt(1)
	v_mfma_f32_32x32x16_bf16 v[114:129], v[82:85], v[150:153], v[114:129]
	s_waitcnt lgkmcnt(0)
	v_mfma_f32_32x32x16_bf16 v[98:113], v[182:185], v[150:153], v[98:113]
	ds_read_b128 v[82:85], v214 offset:32768
	ds_read_b128 v[182:185], v214 offset:40960
	s_waitcnt lgkmcnt(1)
	v_mfma_f32_32x32x16_bf16 v[114:129], v[82:85], v[134:137], v[114:129]
	s_waitcnt lgkmcnt(0)
	v_mfma_f32_32x32x16_bf16 v[98:113], v[182:185], v[134:137], v[98:113]
	ds_read_b128 v[82:85], v211 offset:32896
	ds_read_b128 v[182:185], v211 offset:41088
	s_waitcnt lgkmcnt(1)
	v_mfma_f32_32x32x16_bf16 v[114:129], v[82:85], v[138:141], v[114:129]
	s_waitcnt lgkmcnt(0)
	v_mfma_f32_32x32x16_bf16 v[98:113], v[182:185], v[138:141], v[98:113]
	ds_read_b128 v[82:85], v212 offset:32896
	ds_read_b128 v[182:185], v212 offset:41088
	s_waitcnt lgkmcnt(1)
	v_mfma_f32_32x32x16_bf16 v[114:129], v[82:85], v[142:145], v[114:129]
	s_waitcnt lgkmcnt(0)
	v_mfma_f32_32x32x16_bf16 v[98:113], v[182:185], v[142:145], v[98:113]
	ds_read_b128 v[82:85], v213 offset:32896
	ds_read_b128 v[182:185], v213 offset:41088
	s_waitcnt lgkmcnt(1)
	v_mfma_f32_32x32x16_bf16 v[114:129], v[82:85], v[146:149], v[114:129]
	s_waitcnt lgkmcnt(0)
	v_mfma_f32_32x32x16_bf16 v[98:113], v[182:185], v[146:149], v[98:113]
	ds_read_b128 v[82:85], v214 offset:32896
	ds_read_b128 v[182:185], v214 offset:41088
	s_waitcnt lgkmcnt(1)
	v_mfma_f32_32x32x16_bf16 v[114:129], v[82:85], v[130:133], v[114:129]
	v_exp_f32_e32 v85, v97
	v_exp_f32_e32 v97, v178
	v_add_f32_e32 v178, 0, v66
	v_add_f32_e32 v178, v67, v178
	v_add_f32_e32 v178, v68, v178
	v_add_f32_e32 v178, v69, v178
	v_add_f32_e32 v178, v70, v178
	v_add_f32_e32 v178, v71, v178
	v_add_f32_e32 v178, v72, v178
	v_add_f32_e32 v178, v73, v178
	v_add_f32_e32 v178, v74, v178
	v_add_f32_e32 v178, v75, v178
	v_add_f32_e32 v178, v76, v178
	v_add_f32_e32 v178, v77, v178
	v_exp_f32_e32 v82, v86
	v_add_f32_e32 v178, v78, v178
	v_exp_f32_e32 v83, v95
	v_add_f32_e32 v178, v79, v178
	v_exp_f32_e32 v84, v96
	v_add_f32_e32 v178, v80, v178
	v_add_f32_e32 v178, v81, v178
	v_exp_f32_e32 v86, v179
	v_add_f32_e32 v178, v82, v178
	v_add_f32_e32 v178, v83, v178
	v_add_f32_e32 v178, v84, v178
	v_add_f32_e32 v178, v85, v178
	v_add_f32_e32 v178, v86, v178
	v_add_f32_e32 v178, v87, v178
	v_add_f32_e32 v178, v88, v178
	v_add_f32_e32 v178, v89, v178
	v_add_f32_e32 v178, v90, v178
	v_exp_f32_e32 v95, v180
	v_add_f32_e32 v178, v91, v178
	s_waitcnt lgkmcnt(0)
	v_mfma_f32_32x32x16_bf16 v[98:113], v[182:185], v[130:133], v[98:113]
	v_exp_f32_e32 v96, v181
	v_add_f32_e32 v178, v92, v178
	v_add_f32_e32 v178, v93, v178
	v_add_f32_e32 v178, v94, v178
	v_add_f32_e32 v178, v95, v178
	v_add_f32_e32 v178, v96, v178
	v_add_f32_e32 v228, v97, v178
	v_mov_b32_e32 v229, v228
	v_cvt_pk_bf16_f32 v178, v66, v67
	v_cvt_pk_bf16_f32 v179, v68, v69
	v_cvt_pk_bf16_f32 v180, v70, v71
	v_cvt_pk_bf16_f32 v181, v72, v73
	v_cvt_pk_bf16_f32 v182, v74, v75
	v_cvt_pk_bf16_f32 v183, v76, v77
	v_cvt_pk_bf16_f32 v184, v78, v79
	v_cvt_pk_bf16_f32 v185, v80, v81
	v_cvt_pk_bf16_f32 v186, v82, v83
	v_cvt_pk_bf16_f32 v187, v84, v85
	v_cvt_pk_bf16_f32 v188, v86, v87
	v_cvt_pk_bf16_f32 v192, v94, v95
	v_cvt_pk_bf16_f32 v193, v96, v97
	v_permlane32_swap_b32_e32 v228, v229
	v_permlane32_swap_b32_e32 v178, v180
	v_permlane32_swap_b32_e32 v179, v181
	v_permlane32_swap_b32_e32 v182, v184
	v_permlane32_swap_b32_e32 v183, v185
	v_permlane32_swap_b32_e32 v186, v188
	v_permlane32_swap_b32_e32 v187, v189
	v_permlane32_swap_b32_e32 v190, v192
	v_permlane32_swap_b32_e32 v191, v193
	s_add_i32 s4, s25, 1
	s_cmp_le_u32 s4, s24
	s_cselect_b64 s[76:77], -1, 0
	s_cmp_gt_u32 s4, s24
	s_cbranch_scc1 .LBB0_1137
	v_add_u32_e32 v162, 0x2000, v194
	v_mov_b32_e32 v163, v195
	v_add_u32_e32 v164, 0x3000, v194
	v_mov_b32_e32 v165, v195
	v_lshlrev_b64 v[170:171], 1, v[162:163]
	v_lshlrev_b64 v[172:173], 1, v[164:165]
	v_lshl_add_u64 v[162:163], s[42:43], 0, v[170:171]
	v_lshl_add_u64 v[166:167], s[42:43], 0, v[172:173]
	v_lshl_add_u64 v[170:171], s[22:23], 0, v[170:171]
	v_lshl_add_u64 v[174:175], s[22:23], 0, v[172:173]
	global_load_dwordx4 v[162:165], v[162:163], off
	s_nop 0
	global_load_dwordx4 v[166:169], v[166:167], off
	s_nop 0
	global_load_dwordx4 v[170:173], v[170:171], off
	s_nop 0
	global_load_dwordx4 v[174:177], v[174:175], off
; __device__ __forceinline__ void mask_tile(f32x16& p0, f32x16& p1, int dq, unsigned W) {
;     const float NEG = -__builtin_inff();
; #pragma unroll
;     for (int r = 0; r < 16; ++r) {
;         const int c = (r & 3) + 8 * (r >> 2);
;         if ((unsigned)(dq - c) >= W) p0[r] = NEG;
;         if ((unsigned)(dq - c - 32) >= W) p1[r] = NEG;
;     }
; }
; template <int VB, bool SK>
; __device__ __forceinline__ void pv_tile(f32x16* o, int vb0, bf16x8 pa0, bf16x8 pa1, bf16x8 pa2, bf16x8 pa3, bool act) {
;     if (SK && !act) return;
.LBB0_1137:
	s_sub_i32 s27, s26, 63
	s_cmp_le_i32 s26, s13
	s_cselect_b64 s[4:5], -1, 0
	s_cmp_gt_i32 s27, s15
	s_cselect_b64 s[52:53], -1, 0
	s_and_b64 s[4:5], s[4:5], s[52:53]
	s_and_b64 vcc, exec, s[4:5]
	ds_read_b64_tr_b16 v[230:231], v202 offset:0x4000
	ds_read_b64_tr_b16 v[232:233], v202 offset:0x4800
	ds_read_b64_tr_b16 v[234:235], v202 offset:0x5000
	ds_read_b64_tr_b16 v[236:237], v202 offset:0x5800
	ds_read_b64_tr_b16 v[238:239], v202 offset:0x6000
	ds_read_b64_tr_b16 v[240:241], v202 offset:0x6800
	ds_read_b64_tr_b16 v[242:243], v202 offset:0x7000
	ds_read_b64_tr_b16 v[244:245], v202 offset:0x7800
	s_cbranch_vccnz .Lh2_nomask
	v_add_u32_e32 v66, 0xffffff80, v226
	v_cmp_gt_u32_e32 vcc, s85, v66
	v_add_u32_e32 v66, 0xffffff60, v226
	s_nop 0
	v_cndmask_b32_e32 v114, v215, v114, vcc
	v_cmp_gt_u32_e32 vcc, s85, v66
	v_add_u32_e32 v66, 0xffffff7f, v226
	s_nop 0
	v_cndmask_b32_e32 v98, v215, v98, vcc
	v_cmp_gt_u32_e32 vcc, s85, v66
	v_add_u32_e32 v66, 0xffffff5f, v226
	s_nop 0
	v_cndmask_b32_e32 v115, v215, v115, vcc
	v_cmp_gt_u32_e32 vcc, s85, v66
	v_add_u32_e32 v66, 0xffffff7e, v226
	s_nop 0
	v_cndmask_b32_e32 v99, v215, v99, vcc
	v_cmp_gt_u32_e32 vcc, s85, v66
	v_add_u32_e32 v66, 0xffffff5e, v226
	s_nop 0
	v_cndmask_b32_e32 v116, v215, v116, vcc
	v_cmp_gt_u32_e32 vcc, s85, v66
	v_add_u32_e32 v66, 0xffffff7d, v226
	s_nop 0
	v_cndmask_b32_e32 v100, v215, v100, vcc
	v_cmp_gt_u32_e32 vcc, s85, v66
	v_add_u32_e32 v66, 0xffffff5d, v226
	s_nop 0
	v_cndmask_b32_e32 v117, v215, v117, vcc
	v_cmp_gt_u32_e32 vcc, s85, v66
	v_add_u32_e32 v66, 0xffffff78, v226
	s_nop 0
	v_cndmask_b32_e32 v101, v215, v101, vcc
	v_cmp_gt_u32_e32 vcc, s85, v66
	v_add_u32_e32 v66, 0xffffff58, v226
	s_nop 0
	v_cndmask_b32_e32 v118, v215, v118, vcc
	v_cmp_gt_u32_e32 vcc, s85, v66
	v_add_u32_e32 v66, 0xffffff77, v226
	s_nop 0
	v_cndmask_b32_e32 v102, v215, v102, vcc
	v_cmp_gt_u32_e32 vcc, s85, v66
	v_add_u32_e32 v66, 0xffffff57, v226
	s_nop 0
	v_cndmask_b32_e32 v119, v215, v119, vcc
	v_cmp_gt_u32_e32 vcc, s85, v66
	v_add_u32_e32 v66, 0xffffff76, v226
	s_nop 0
	v_cndmask_b32_e32 v103, v215, v103, vcc
	v_cmp_gt_u32_e32 vcc, s85, v66
	v_add_u32_e32 v66, 0xffffff56, v226
	s_nop 0
	v_cndmask_b32_e32 v120, v215, v120, vcc
	v_cmp_gt_u32_e32 vcc, s85, v66
	v_add_u32_e32 v66, 0xffffff75, v226
	s_nop 0
	v_cndmask_b32_e32 v104, v215, v104, vcc
	v_cmp_gt_u32_e32 vcc, s85, v66
	v_add_u32_e32 v66, 0xffffff55, v226
	s_nop 0
	v_cndmask_b32_e32 v121, v215, v121, vcc
	v_cmp_gt_u32_e32 vcc, s85, v66
	v_add_u32_e32 v66, 0xffffff70, v226
	s_nop 0
	v_cndmask_b32_e32 v105, v215, v105, vcc
	v_cmp_gt_u32_e32 vcc, s85, v66
	v_add_u32_e32 v66, 0xffffff50, v226
	s_nop 0
	v_cndmask_b32_e32 v122, v215, v122, vcc
	v_cmp_gt_u32_e32 vcc, s85, v66
	v_add_u32_e32 v66, 0xffffff6f, v226
	s_nop 0
	v_cndmask_b32_e32 v106, v215, v106, vcc
	v_cmp_gt_u32_e32 vcc, s85, v66
	v_add_u32_e32 v66, 0xffffff4f, v226
	s_nop 0
	v_cndmask_b32_e32 v123, v215, v123, vcc
	v_cmp_gt_u32_e32 vcc, s85, v66
	v_add_u32_e32 v66, 0xffffff6e, v226
	s_nop 0
	v_cndmask_b32_e32 v107, v215, v107, vcc
	v_cmp_gt_u32_e32 vcc, s85, v66
	v_add_u32_e32 v66, 0xffffff4e, v226
	s_nop 0
	v_cndmask_b32_e32 v124, v215, v124, vcc
	v_cmp_gt_u32_e32 vcc, s85, v66
	v_add_u32_e32 v66, 0xffffff6d, v226
	s_nop 0
	v_cndmask_b32_e32 v108, v215, v108, vcc
	v_cmp_gt_u32_e32 vcc, s85, v66
	v_add_u32_e32 v66, 0xffffff4d, v226
	s_nop 0
	v_cndmask_b32_e32 v125, v215, v125, vcc
	v_cmp_gt_u32_e32 vcc, s85, v66
	v_add_u32_e32 v66, 0xffffff68, v226
	s_nop 0
	v_cndmask_b32_e32 v109, v215, v109, vcc
	v_cmp_gt_u32_e32 vcc, s85, v66
	v_add_u32_e32 v66, 0xffffff48, v226
	s_nop 0
	v_cndmask_b32_e32 v126, v215, v126, vcc
	v_cmp_gt_u32_e32 vcc, s85, v66
	v_add_u32_e32 v66, 0xffffff67, v226
	s_nop 0
	v_cndmask_b32_e32 v110, v215, v110, vcc
	v_cmp_gt_u32_e32 vcc, s85, v66
	v_add_u32_e32 v66, 0xffffff47, v226
	s_nop 0
	v_cndmask_b32_e32 v127, v215, v127, vcc
	v_cmp_gt_u32_e32 vcc, s85, v66
	v_add_u32_e32 v66, 0xffffff66, v226
	s_nop 0
	v_cndmask_b32_e32 v111, v215, v111, vcc
	v_cmp_gt_u32_e32 vcc, s85, v66
	v_add_u32_e32 v66, 0xffffff46, v226
	s_nop 0
	v_cndmask_b32_e32 v128, v215, v128, vcc
	v_cmp_gt_u32_e32 vcc, s85, v66
	v_add_u32_e32 v66, 0xffffff65, v226
	s_nop 0
	v_cndmask_b32_e32 v112, v215, v112, vcc
	v_cmp_gt_u32_e32 vcc, s85, v66
	v_add_u32_e32 v66, 0xffffff45, v226
	s_nop 0
	v_cndmask_b32_e32 v129, v215, v129, vcc
	v_cmp_gt_u32_e32 vcc, s85, v66
	s_nop 1
	v_cndmask_b32_e32 v113, v215, v113, vcc
; __device__ __forceinline__ void partialSM(f32x16& p0, f32x16& p1, float& m_reg, float& mn, float& alpha) {
;     float pmax = p0[0]; for (int r = 1; r < 16; ++r) pmax = fmaxf(pmax, p0[r]); for (int r = 0; r < 16; ++r) pmax = fmaxf(pmax, p1[r]);
;     { auto rr = __builtin_amdgcn_permlane32_swap(__float_as_uint(pmax), __float_as_uint(pmax), false, false);
;       pmax = fmaxf(__uint_as_float(rr[0]), __uint_as_float(rr[1])); }
;     constexpr float C2 = 1.4426950408889634f * SCALE;
;     if (__builtin_expect(__all((pmax - m_reg) * SCALE <= THR), 1)) { mn = m_reg; alpha = 1.f; }
;     else { mn = fmaxf(m_reg, pmax); alpha = __builtin_amdgcn_exp2f((m_reg - mn) * C2); m_reg = mn; }
;     const float mnL = -mn * C2;
;     for (int r = 0; r < 16; ++r) p0[r] = fmaf(p0[r], C2, mnL); for (int r = 0; r < 16; ++r) p1[r] = fmaf(p1[r], C2, mnL);
;     for (int r = 0; r < 16; ++r) p0[r] = __builtin_amdgcn_exp2f(p0[r]);
; }
; __device__ __forceinline__ void finishSM(f32x16& p0, f32x16& p1, float alpha, float& l_reg, bf16x8& pa0, bf16x8& pa1, bf16x8& pa2, bf16x8& pa3) {
;     for (int r = 0; r < 16; ++r) p1[r] = __builtin_amdgcn_exp2f(p1[r]);
;     float ps = 0; for (int r = 0; r < 16; ++r) ps += p0[r]; for (int r = 0; r < 16; ++r) ps += p1[r];
;     { auto rr = __builtin_amdgcn_permlane32_swap(__float_as_uint(ps), __float_as_uint(ps), false, false);
;       ps = __uint_as_float(rr[0]) + __uint_as_float(rr[1]); }
;     l_reg = l_reg * alpha + ps;
; template <int VB, bool SK>
; __device__ __forceinline__ void pv_tile(f32x16* o, int vb0, bf16x8 pa0, bf16x8 pa1, bf16x8 pa2, bf16x8 pa3, bool act) {
;     if (SK && !act) return;
;     ...
;     PV_D0(0); PV_D0(1); PV_D0(2); PV_D0(3);
.Lh2_nomask:
	v_max_f32_e32 v66, v115, v115
	v_max_f32_e32 v67, v114, v114
	v_max_f32_e32 v66, v67, v66
	v_max3_f32 v66, v66, v116, v117
	v_max3_f32 v66, v66, v118, v119
	s_waitcnt lgkmcnt(6)
	v_mfma_f32_32x32x16_bf16 v[34:49], v[178:181], v[230:233], v[34:49]
	ds_read_b64_tr_b16 v[230:231], v202 offset:0x4200
	ds_read_b64_tr_b16 v[232:233], v202 offset:0x4a00
	v_max3_f32 v66, v66, v120, v121
	v_max3_f32 v66, v66, v122, v123
	v_max3_f32 v66, v66, v124, v125
	v_max3_f32 v66, v66, v126, v127
	v_max3_f32 v66, v66, v128, v129
	s_waitcnt lgkmcnt(6)
	v_mfma_f32_32x32x16_bf16 v[34:49], v[182:185], v[234:237], v[34:49]
	ds_read_b64_tr_b16 v[234:235], v202 offset:0x5200
	ds_read_b64_tr_b16 v[236:237], v202 offset:0x5a00
	v_max3_f32 v66, v66, v98, v99
	v_max3_f32 v66, v66, v100, v101
	v_max3_f32 v66, v66, v102, v103
	v_max3_f32 v66, v66, v104, v105
	v_max3_f32 v66, v66, v106, v107
	s_waitcnt lgkmcnt(6)
	v_mfma_f32_32x32x16_bf16 v[34:49], v[186:189], v[238:241], v[34:49]
	ds_read_b64_tr_b16 v[238:239], v202 offset:0x6200
	ds_read_b64_tr_b16 v[240:241], v202 offset:0x6a00
	v_max3_f32 v66, v66, v108, v109
	v_max3_f32 v66, v66, v110, v111
	v_max3_f32 v66, v66, v112, v113
	v_mov_b32_e32 v67, v66
	s_nop 1
	v_permlane32_swap_b32_e32 v66, v67
	s_waitcnt lgkmcnt(6)
	v_mfma_f32_32x32x16_bf16 v[34:49], v[190:193], v[242:245], v[34:49]
	ds_read_b64_tr_b16 v[242:243], v202 offset:0x7200
	ds_read_b64_tr_b16 v[244:245], v202 offset:0x7a00
	v_max_f32_e32 v67, v67, v67
	v_max_f32_e32 v66, v66, v66
	v_max_f32_e32 v66, v66, v67
	v_sub_f32_e32 v67, v66, v227
	v_max_f32_e32 v84, v227, v227
	s_waitcnt lgkmcnt(6)
	v_mfma_f32_32x32x16_bf16 v[50:65], v[178:181], v[230:233], v[50:65]
	ds_read_b64_tr_b16 v[230:231], v202 offset:0x4400
	ds_read_b64_tr_b16 v[232:233], v202 offset:0x4c00
	v_mul_f32_e32 v67, 0x3db504f3, v67
	v_max_f32_e32 v84, v84, v66
	v_cmp_ge_f32_e32 vcc, s86, v67
	s_cmp_eq_u64 vcc, exec
	s_cselect_b64 s[4:5], -1, 0
	v_sub_f32_e32 v85, v227, v84
	s_waitcnt lgkmcnt(6)
	v_mfma_f32_32x32x16_bf16 v[50:65], v[182:185], v[234:237], v[50:65]
	ds_read_b64_tr_b16 v[234:235], v202 offset:0x5400
	ds_read_b64_tr_b16 v[236:237], v202 offset:0x5c00
	v_cndmask_b32_e64 v88, v84, v227, s[4:5]
	v_mul_f32_e32 v85, 0x3e0293ee, v85
	v_mul_f32_e32 v86, 0xbe0293ee, v88
	v_exp_f32_e32 v85, v85
	s_waitcnt lgkmcnt(6)
	v_mfma_f32_32x32x16_bf16 v[50:65], v[186:189], v[238:241], v[50:65]
	ds_read_b64_tr_b16 v[238:239], v202 offset:0x6400
	ds_read_b64_tr_b16 v[240:241], v202 offset:0x6c00
	v_fmamk_f32 v68, v114, 0x3e0293ee, v86
	v_fmamk_f32 v69, v115, 0x3e0293ee, v86
	v_fmamk_f32 v70, v116, 0x3e0293ee, v86
	v_fmamk_f32 v71, v117, 0x3e0293ee, v86
	s_waitcnt lgkmcnt(6)
	v_mfma_f32_32x32x16_bf16 v[50:65], v[190:193], v[242:245], v[50:65]
	ds_read_b64_tr_b16 v[242:243], v202 offset:0x7400
	ds_read_b64_tr_b16 v[244:245], v202 offset:0x7c00
	v_fmamk_f32 v79, v118, 0x3e0293ee, v86
	v_fmamk_f32 v80, v119, 0x3e0293ee, v86
	v_fmamk_f32 v72, v120, 0x3e0293ee, v86
	v_fmamk_f32 v73, v121, 0x3e0293ee, v86
	s_waitcnt lgkmcnt(6)
	v_mfma_f32_32x32x16_bf16 v[18:33], v[178:181], v[230:233], v[18:33]
	ds_read_b64_tr_b16 v[230:231], v202 offset:0x4600
	ds_read_b64_tr_b16 v[232:233], v202 offset:0x4e00
	v_fmamk_f32 v81, v122, 0x3e0293ee, v86
	v_fmamk_f32 v82, v123, 0x3e0293ee, v86
	v_fmamk_f32 v74, v124, 0x3e0293ee, v86
	v_fmamk_f32 v75, v125, 0x3e0293ee, v86
	s_waitcnt lgkmcnt(6)
	v_mfma_f32_32x32x16_bf16 v[18:33], v[182:185], v[234:237], v[18:33]
	ds_read_b64_tr_b16 v[234:235], v202 offset:0x5600
	ds_read_b64_tr_b16 v[236:237], v202 offset:0x5e00
	v_fmamk_f32 v76, v126, 0x3e0293ee, v86
	v_fmamk_f32 v77, v127, 0x3e0293ee, v86
	v_fmamk_f32 v83, v128, 0x3e0293ee, v86
	v_fmamk_f32 v78, v129, 0x3e0293ee, v86
	s_waitcnt lgkmcnt(6)
	v_mfma_f32_32x32x16_bf16 v[18:33], v[186:189], v[238:241], v[18:33]
	ds_read_b64_tr_b16 v[238:239], v202 offset:0x6600
	ds_read_b64_tr_b16 v[240:241], v202 offset:0x6e00
	v_fmamk_f32 v126, v98, 0x3e0293ee, v86
	v_fmamk_f32 v127, v99, 0x3e0293ee, v86
	v_fmamk_f32 v124, v100, 0x3e0293ee, v86
	v_fmamk_f32 v125, v101, 0x3e0293ee, v86
	s_waitcnt lgkmcnt(6)
	v_mfma_f32_32x32x16_bf16 v[18:33], v[190:193], v[242:245], v[18:33]
	ds_read_b64_tr_b16 v[242:243], v202 offset:0x7600
	ds_read_b64_tr_b16 v[244:245], v202 offset:0x7e00
	v_fmamk_f32 v120, v102, 0x3e0293ee, v86
	v_fmamk_f32 v121, v103, 0x3e0293ee, v86
	v_fmamk_f32 v116, v104, 0x3e0293ee, v86
	v_fmamk_f32 v117, v105, 0x3e0293ee, v86
	s_waitcnt lgkmcnt(6)
	v_mfma_f32_32x32x16_bf16 v[2:17], v[178:181], v[230:233], v[2:17]
	v_fmamk_f32 v114, v106, 0x3e0293ee, v86
	v_fmamk_f32 v115, v107, 0x3e0293ee, v86
	v_fmamk_f32 v128, v108, 0x3e0293ee, v86
	v_fmamk_f32 v129, v109, 0x3e0293ee, v86
	s_waitcnt lgkmcnt(4)
	v_mfma_f32_32x32x16_bf16 v[2:17], v[182:185], v[234:237], v[2:17]
	v_fmamk_f32 v122, v110, 0x3e0293ee, v86
	v_fmamk_f32 v123, v111, 0x3e0293ee, v86
	v_fmamk_f32 v118, v112, 0x3e0293ee, v86
	v_fmamk_f32 v119, v113, 0x3e0293ee, v86
	s_waitcnt lgkmcnt(2)
	v_mfma_f32_32x32x16_bf16 v[2:17], v[186:189], v[238:241], v[2:17]
	v_add_f32_e32 v98, v223, v224
	v_fmac_f32_e32 v98, v197, v221
	v_add_f32_e32 v221, v228, v229
	v_fmac_f32_e32 v221, v98, v225
	s_waitcnt lgkmcnt(0)
	v_mfma_f32_32x32x16_bf16 v[2:17], v[190:193], v[242:245], v[2:17]
	v_cndmask_b32_e64 v179, v85, 1.0, s[4:5]
	v_cndmask_b32_e64 v178, v84, v227, s[4:5]
	s_andn2_b64 vcc, exec, s[76:77]
	s_barrier
	s_cbranch_vccnz .Lh2_nowrite
	s_waitcnt vmcnt(0)
	ds_write_b128 v209, v[162:165] offset:16384
	ds_write_b128 v210, v[166:169] offset:16384
	ds_write_b128 v217, v[170:173] offset:49152
	ds_write_b128 v217, v[174:177] offset:57344
; #define SBAR() __builtin_amdgcn_sched_barrier(0)
; #define VMW() asm volatile("s_waitcnt vmcnt(0)" ::: "memory")
; #define SLOAD_H(Kp, Vp, k0) do { S.st_v0 = load8<TIn>(ROW(Vp, k0, sr)); S.st_v1 = load8<TIn>(ROW(Vp, k0, 32 + sr));              \
;                          S.st_k0 = load8<TIn>(ROW(Kp, k0, sr)); S.st_k1 = load8<TIn>(ROW(Kp, k0, 32 + sr)); } while (0)
; #define SWRITE_HV(bf) do { *(bf16x8*)(V_lds + (bf) * SHM_V + vst0) = S.st_v0; *(bf16x8*)(V_lds + (bf) * SHM_V + vst1) = S.st_v1; } while (0)
; #define SWRITE_H(bf) do { SWRITE_HV(bf); SWRITE_HK(bf); } while (0)
; #define SLOAD_F(p, k0) do { S.sf0 = *(const f32x4*)ROW(p, k0, sr); S.sf1 = *(const f32x4*)(ROW(p, k0, sr) + 4);                \
;                             S.sf2 = *(const f32x4*)ROW(p, k0, 32 + sr); S.sf3 = *(const f32x4*)(ROW(p, k0, 32 + sr) + 4); } while (0)
; #define ACT(t) (KBASE(t) <= qlo + QBLK - 1 && KBASE(t) + KVBLK - 1 >= qlo - W + 1)
; __device__ __forceinline__ void partialSM(f32x16& p0, f32x16& p1, float& m_reg, float& mn, float& alpha) {
;     ...
;     for (int r = 0; r < 16; ++r) p0[r] = fmaf(p0[r], C2, mnL); for (int r = 0; r < 16; ++r) p1[r] = fmaf(p1[r], C2, mnL);
;     for (int r = 0; r < 16; ++r) p0[r] = __builtin_amdgcn_exp2f(p0[r]);
; template <class TIn, class TOut>
; __device__ __forceinline__ void causal_swa_block(const BlockRef<TIn, TOut>& cur, const BlockRef<TIn, TOut>& nxt, int skv, int W, char* lds, Seam<TIn>& S) {
;     ...
;     constexpr int NQL = F32 ? 16 : 8;
;     constexpr bool SK = WSKIP && !F32;
;     ...
;     f32x16 pA0, pA1, pB0, pB1; float mnA, mnB, alA, alB; bf16x8 pa0, pa1, pa2, pa3;
;     if constexpr (F32) { VMW(); SWRITE_VF(0); SBAR(); } else { SWRITE_HV(0); SBAR(); }
;     if (NT > 1) { if constexpr (F32) SLOAD_F((const float*)Kh, KBASE(1)); else SLOAD_H(Kh, Vh, KBASE(1)); }
;     SBAR(); qkt<0, SK>(pA0, pA1, K_lds, r32, hi, S.qr, ACT(0));
;     if constexpr (F32) { if (NT > 1) { VMW(); SWRITE_KF(1); SBAR(); SLOAD_F((const float*)Vh, KBASE(1)); } }
;     MASKT(pA0, pA1, 0); partialSM(pA0, pA1, m_reg, mnA, alA);
;     if (NT > 1) { VMW(); if constexpr (F32) { SWRITE_VF(1); SBAR(); if (NT > 2) SLOAD_F((const float*)Kh, KBASE(2)); } else SWRITE_H(1); }
;     __syncthreads();
;     ...
;     for (int t = 1; t + 1 < NT; t += 2) {
;         HALF_STEP(pB0, pB1, mnB, alB, pA0, pA1, alA, t, 1, 0, 0);
;         HALF_STEP(pA0, pA1, mnA, alA, pB0, pB1, alB, t + 1, 0, 1, 1);
;     }
.Lh2_nowrite:
	v_cmp_gt_f32_e32 vcc, 1.0, v179
	v_add_u32_e32 v194, 0x4000, v194
	v_add_u32_e32 v222, 0xffffff80, v222
	s_addk_i32 s26, 0x80
	s_add_i32 s25, s25, 2
	s_nop 1
	s_cbranch_vccz .Lh2_noresc
	s_and_saveexec_b64 s[52:53], s[0:1]
	ds_write_b32 v219, v179 offset:128
	s_or_b64 exec, exec, s[52:53]
	s_waitcnt lgkmcnt(0)
	ds_read_b128 v[164:167], v218 offset:224
	ds_read_b128 v[168:171], v218 offset:192
	ds_read_b128 v[172:175], v218 offset:160
	ds_read_b128 v[180:183], v218 offset:128
	s_waitcnt lgkmcnt(3)
	v_pk_mul_f32 v[48:49], v[48:49], v[166:167]
	s_waitcnt lgkmcnt(2)
	v_pk_mul_f32 v[44:45], v[44:45], v[170:171]
	s_waitcnt lgkmcnt(1)
	v_pk_mul_f32 v[40:41], v[40:41], v[174:175]
	s_waitcnt lgkmcnt(0)
	v_pk_mul_f32 v[36:37], v[36:37], v[182:183]
	v_pk_mul_f32 v[46:47], v[46:47], v[164:165]
	v_pk_mul_f32 v[42:43], v[42:43], v[168:169]
	v_pk_mul_f32 v[38:39], v[38:39], v[172:173]
	v_pk_mul_f32 v[34:35], v[34:35], v[180:181]
	v_pk_mul_f32 v[64:65], v[64:65], v[166:167]
	v_pk_mul_f32 v[60:61], v[60:61], v[170:171]
	v_pk_mul_f32 v[56:57], v[56:57], v[174:175]
	v_pk_mul_f32 v[52:53], v[52:53], v[182:183]
	v_pk_mul_f32 v[62:63], v[62:63], v[164:165]
	v_pk_mul_f32 v[58:59], v[58:59], v[168:169]
	v_pk_mul_f32 v[54:55], v[54:55], v[172:173]
	v_pk_mul_f32 v[50:51], v[50:51], v[180:181]
	v_pk_mul_f32 v[32:33], v[32:33], v[166:167]
	v_pk_mul_f32 v[28:29], v[28:29], v[170:171]
	v_pk_mul_f32 v[24:25], v[24:25], v[174:175]
	v_pk_mul_f32 v[20:21], v[20:21], v[182:183]
	v_pk_mul_f32 v[30:31], v[30:31], v[164:165]
	v_pk_mul_f32 v[26:27], v[26:27], v[168:169]
	v_pk_mul_f32 v[22:23], v[22:23], v[172:173]
	v_pk_mul_f32 v[18:19], v[18:19], v[180:181]
	v_pk_mul_f32 v[16:17], v[16:17], v[166:167]
	v_pk_mul_f32 v[12:13], v[12:13], v[170:171]
	v_pk_mul_f32 v[8:9], v[8:9], v[174:175]
	v_pk_mul_f32 v[4:5], v[4:5], v[182:183]
	v_pk_mul_f32 v[14:15], v[14:15], v[164:165]
	v_pk_mul_f32 v[10:11], v[10:11], v[168:169]
	v_pk_mul_f32 v[6:7], v[6:7], v[172:173]
	v_pk_mul_f32 v[2:3], v[2:3], v[180:181]
.Lh2_noresc:
	v_exp_f32_e32 v170, v68
	v_exp_f32_e32 v171, v69
	v_exp_f32_e32 v172, v70
	v_exp_f32_e32 v173, v71
	v_exp_f32_e32 v174, v79
	v_exp_f32_e32 v176, v80
	v_exp_f32_e32 v175, v72
	v_exp_f32_e32 v177, v73
	v_exp_f32_e32 v162, v81
	v_exp_f32_e32 v163, v82
	v_exp_f32_e32 v164, v74
	v_exp_f32_e32 v166, v75
	v_exp_f32_e32 v165, v76
	v_exp_f32_e32 v167, v77
	v_exp_f32_e32 v168, v83
	v_exp_f32_e32 v169, v78
	s_cmp_gt_u32 s25, s24
	s_waitcnt lgkmcnt(0)
	s_barrier
	s_cbranch_scc1 .LBB0_1147
	v_mov_b32_e32 v197, v179
	s_branch .LBB0_1129
